# up-projection epilogue: packed f32 ops (v_pk_fma/v_pk_mul) for the conv centre tap and the GELU polynomial
# baseline (speedup 1.0000x reference)
.LBB0_1151:
	v_readlane_b32 s51, v251, 4
	s_andn2_b64 vcc, exec, s[40:41]
	s_cbranch_vccnz .LBB0_1173
	s_nop 7
	s_nop 7
	v_lshl_or_b32 v176, s38, 7, v206
	v_lshlrev_b32_e32 v177, 2, v176
	v_add_u32_e32 v178, 0x5800, v177
	v_add_u32_e32 v179, 0xb000, v177
	global_load_dwordx4 v[102:105], v177, s[20:21]
	global_load_dwordx4 v[106:109], v177, s[20:21] offset:16
	global_load_dwordx4 v[110:113], v178, s[20:21]
	global_load_dwordx4 v[114:117], v178, s[20:21] offset:16
	global_load_dwordx4 v[118:121], v179, s[20:21]
	global_load_dwordx4 v[122:125], v179, s[20:21] offset:16
	global_load_dwordx4 v[126:129], v177, s[22:23]
	global_load_dwordx4 v[80:83], v177, s[22:23] offset:16
	v_lshlrev_b32_e32 v175, 1, v176
	s_lshl_b32 s40, s58, 8
	s_add_i32 s40, s40, s70
	s_movk_i32 s44, 0x2c00
	v_or_b32_e32 v174, s40, v192
	v_mov_b32_e32 v208, 0xbdd2d3e7
	s_mov_b32 s42, s31
	s_mov_b32 s43, s90
	s_ashr_i32 s41, s40, 4
	s_and_saveexec_b64 s[38:39], s[12:13]
	v_or_b32_e32 v176, s41, v192
	v_mad_u32_u24 v176, v176, s44, v175
	v_cvt_pk_bf16_f32 v188, v92, v93
	v_cvt_pk_bf16_f32 v189, v94, v95
	v_cvt_pk_bf16_f32 v190, v84, v85
	v_cvt_pk_bf16_f32 v191, v86, v87
	global_store_dwordx4 v176, v[188:191], s[62:63]
	s_and_b64 exec, exec, s[4:5]
	s_ashr_i32 s41, s40, 5
	s_mul_i32 s41, s41, s44
	v_add_u32_e32 v177, s41, v175
	v_cvt_pk_bf16_f32 v180, v98, v99
	v_cvt_pk_bf16_f32 v181, v100, v101
	v_cvt_pk_bf16_f32 v182, v88, v89
	v_cvt_pk_bf16_f32 v183, v90, v91
	global_store_dwordx4 v177, v[180:183], s[42:43]
	s_or_b64 exec, exec, s[38:39]
	s_ashr_i32 s41, s40, 4
	s_and_saveexec_b64 s[38:39], s[14:15]
	v_add_u32_e32 v178, s41, v205
	v_mad_u32_u24 v178, v178, s44, v175
	v_cvt_pk_bf16_f32 v184, v72, v73
	v_cvt_pk_bf16_f32 v185, v74, v75
	v_cvt_pk_bf16_f32 v186, v64, v65
	v_cvt_pk_bf16_f32 v187, v66, v67
	global_store_dwordx4 v178, v[184:187], s[62:63]
	s_and_b64 exec, exec, s[8:9]
	s_ashr_i32 s41, s40, 5
	s_or_b32 s41, s41, 1
	s_mul_i32 s41, s41, s44
	v_add_u32_e32 v179, s41, v175
	v_cvt_pk_bf16_f32 v188, v76, v77
	v_cvt_pk_bf16_f32 v189, v78, v79
	v_cvt_pk_bf16_f32 v190, v68, v69
	v_cvt_pk_bf16_f32 v191, v70, v71
	global_store_dwordx4 v179, v[188:191], s[42:43]
	s_or_b64 exec, exec, s[38:39]
	s_addk_i32 s40, 0x80
	s_ashr_i32 s41, s40, 4
	s_and_saveexec_b64 s[38:39], s[12:13]
	v_or_b32_e32 v176, s41, v192
	v_mad_u32_u24 v176, v176, s44, v175
	v_cvt_pk_bf16_f32 v188, v24, v25
	v_cvt_pk_bf16_f32 v189, v26, v27
	v_cvt_pk_bf16_f32 v190, v16, v17
	v_cvt_pk_bf16_f32 v191, v18, v19
	global_store_dwordx4 v176, v[188:191], s[62:63]
	s_and_b64 exec, exec, s[4:5]
	s_ashr_i32 s41, s40, 5
	s_mul_i32 s41, s41, s44
	v_add_u32_e32 v177, s41, v175
	v_cvt_pk_bf16_f32 v180, v28, v29
	v_cvt_pk_bf16_f32 v181, v30, v31
	v_cvt_pk_bf16_f32 v182, v20, v21
	v_cvt_pk_bf16_f32 v183, v22, v23
	global_store_dwordx4 v177, v[180:183], s[42:43]
	s_or_b64 exec, exec, s[38:39]
	s_ashr_i32 s41, s40, 4
	s_and_saveexec_b64 s[38:39], s[14:15]
	v_add_u32_e32 v178, s41, v205
	v_mad_u32_u24 v178, v178, s44, v175
	v_cvt_pk_bf16_f32 v184, v8, v9
	v_cvt_pk_bf16_f32 v185, v10, v11
	v_cvt_pk_bf16_f32 v186, v0, v1
	v_cvt_pk_bf16_f32 v187, v2, v3
	global_store_dwordx4 v178, v[184:187], s[62:63]
	s_and_b64 exec, exec, s[8:9]
	s_ashr_i32 s41, s40, 5
	s_or_b32 s41, s41, 1
	s_mul_i32 s41, s41, s44
	v_add_u32_e32 v179, s41, v175
	v_cvt_pk_bf16_f32 v188, v12, v13
	v_cvt_pk_bf16_f32 v189, v14, v15
	v_cvt_pk_bf16_f32 v190, v4, v5
	v_cvt_pk_bf16_f32 v191, v6, v7
	global_store_dwordx4 v179, v[188:191], s[42:43]
	s_or_b64 exec, exec, s[38:39]
	s_mov_b32 s40, 0xc0135761
	s_waitcnt vmcnt(8)
	v_cndmask_b32_e64 v176, v92, 0, s[8:9]
	v_cndmask_b32_e64 v177, v93, 0, s[8:9]
	v_cndmask_b32_e64 v178, v94, 0, s[8:9]
	v_cndmask_b32_e64 v179, v95, 0, s[8:9]
	v_cndmask_b32_e64 v180, v92, v150, s[4:5]
	v_cndmask_b32_e64 v181, v93, v151, s[4:5]
	v_cndmask_b32_e64 v182, v94, v152, s[4:5]
	v_cndmask_b32_e64 v183, v95, v153, s[4:5]
	v_pk_fma_f32 v[184:185], v[110:111], v[92:93], v[126:127]
	v_pk_fma_f32 v[186:187], v[112:113], v[94:95], v[128:129]
	v_fmac_f32_dpp v184, v176, v102 row_ror:1 row_mask:0xf bank_mask:0xf
	v_fmac_f32_dpp v185, v177, v103 row_ror:1 row_mask:0xf bank_mask:0xf
	v_fmac_f32_dpp v186, v178, v104 row_ror:1 row_mask:0xf bank_mask:0xf
	v_fmac_f32_dpp v187, v179, v105 row_ror:1 row_mask:0xf bank_mask:0xf
	v_fmac_f32_dpp v184, v180, v118 row_ror:15 row_mask:0xf bank_mask:0xf
	v_fmac_f32_dpp v185, v181, v119 row_ror:15 row_mask:0xf bank_mask:0xf
	v_fmac_f32_dpp v186, v182, v120 row_ror:15 row_mask:0xf bank_mask:0xf
	v_fmac_f32_dpp v187, v183, v121 row_ror:15 row_mask:0xf bank_mask:0xf
	v_pk_mul_f32 v[176:177], v[184:185], v[184:185]
	v_pk_mul_f32 v[178:179], v[186:187], v[186:187]
	v_pk_fma_f32 v[176:177], v[176:177], v[208:209], s[40:41] op_sel_hi:[1,0,0]
	v_pk_fma_f32 v[178:179], v[178:179], v[208:209], s[40:41] op_sel_hi:[1,0,0]
	v_pk_mul_f32 v[176:177], v[176:177], v[184:185]
	v_pk_mul_f32 v[178:179], v[178:179], v[186:187]
	v_exp_f32_e32 v176, v176
	v_exp_f32_e32 v177, v177
	v_exp_f32_e32 v178, v178
	v_exp_f32_e32 v179, v179
	v_add_f32_e32 v176, 1.0, v176
	v_add_f32_e32 v177, 1.0, v177
	v_add_f32_e32 v178, 1.0, v178
	v_add_f32_e32 v179, 1.0, v179
	v_rcp_f32_e32 v176, v176
	v_rcp_f32_e32 v177, v177
	v_rcp_f32_e32 v178, v178
	v_rcp_f32_e32 v179, v179
	v_pk_mul_f32 v[184:185], v[184:185], v[176:177]
	v_pk_mul_f32 v[186:187], v[186:187], v[178:179]
	v_pk_mul_f32 v[184:185], v[184:185], v[98:99]
	v_pk_mul_f32 v[186:187], v[186:187], v[100:101]
	v_cvt_pk_bf16_f32 v188, v184, v185
	v_cvt_pk_bf16_f32 v189, v186, v187
	v_cndmask_b32_e64 v176, v84, 0, s[8:9]
	v_cndmask_b32_e64 v177, v85, 0, s[8:9]
	v_cndmask_b32_e64 v178, v86, 0, s[8:9]
	v_cndmask_b32_e64 v179, v87, 0, s[8:9]
	v_cndmask_b32_e64 v180, v84, v142, s[4:5]
	v_cndmask_b32_e64 v181, v85, v143, s[4:5]
	v_cndmask_b32_e64 v182, v86, v144, s[4:5]
	v_cndmask_b32_e64 v183, v87, v145, s[4:5]
	v_pk_fma_f32 v[184:185], v[114:115], v[84:85], v[80:81]
	v_pk_fma_f32 v[186:187], v[116:117], v[86:87], v[82:83]
	v_fmac_f32_dpp v184, v176, v106 row_ror:1 row_mask:0xf bank_mask:0xf
	v_fmac_f32_dpp v185, v177, v107 row_ror:1 row_mask:0xf bank_mask:0xf
	v_fmac_f32_dpp v186, v178, v108 row_ror:1 row_mask:0xf bank_mask:0xf
	v_fmac_f32_dpp v187, v179, v109 row_ror:1 row_mask:0xf bank_mask:0xf
	v_fmac_f32_dpp v184, v180, v122 row_ror:15 row_mask:0xf bank_mask:0xf
	v_fmac_f32_dpp v185, v181, v123 row_ror:15 row_mask:0xf bank_mask:0xf
	v_fmac_f32_dpp v186, v182, v124 row_ror:15 row_mask:0xf bank_mask:0xf
	v_fmac_f32_dpp v187, v183, v125 row_ror:15 row_mask:0xf bank_mask:0xf
	v_pk_mul_f32 v[176:177], v[184:185], v[184:185]
	v_pk_mul_f32 v[178:179], v[186:187], v[186:187]
	v_pk_fma_f32 v[176:177], v[176:177], v[208:209], s[40:41] op_sel_hi:[1,0,0]
	v_pk_fma_f32 v[178:179], v[178:179], v[208:209], s[40:41] op_sel_hi:[1,0,0]
	v_pk_mul_f32 v[176:177], v[176:177], v[184:185]
	v_pk_mul_f32 v[178:179], v[178:179], v[186:187]
	v_exp_f32_e32 v176, v176
	v_exp_f32_e32 v177, v177
	v_exp_f32_e32 v178, v178
	v_exp_f32_e32 v179, v179
	v_add_f32_e32 v176, 1.0, v176
	v_add_f32_e32 v177, 1.0, v177
	v_add_f32_e32 v178, 1.0, v178
	v_add_f32_e32 v179, 1.0, v179
	v_rcp_f32_e32 v176, v176
	v_rcp_f32_e32 v177, v177
	v_rcp_f32_e32 v178, v178
	v_rcp_f32_e32 v179, v179
	v_pk_mul_f32 v[184:185], v[184:185], v[176:177]
	v_pk_mul_f32 v[186:187], v[186:187], v[178:179]
	v_pk_mul_f32 v[184:185], v[184:185], v[88:89]
	v_pk_mul_f32 v[186:187], v[186:187], v[90:91]
	v_cvt_pk_bf16_f32 v190, v184, v185
	v_cvt_pk_bf16_f32 v191, v186, v187
	v_mov_b32_e32 v176, v174
	v_mad_u32_u24 v176, v176, s44, v175
	s_and_saveexec_b64 s[38:39], s[6:7]
	global_store_dwordx4 v176, v[188:191], s[54:55]
	s_or_b64 exec, exec, s[38:39]
	v_cndmask_b32_e64 v176, v150, v92, s[8:9]
	v_cndmask_b32_e64 v177, v151, v93, s[8:9]
	v_cndmask_b32_e64 v178, v152, v94, s[8:9]
	v_cndmask_b32_e64 v179, v153, v95, s[8:9]
	v_cndmask_b32_e64 v180, v150, v134, s[4:5]
	v_cndmask_b32_e64 v181, v151, v135, s[4:5]
	v_cndmask_b32_e64 v182, v152, v136, s[4:5]
	v_cndmask_b32_e64 v183, v153, v137, s[4:5]
	v_pk_fma_f32 v[184:185], v[110:111], v[150:151], v[126:127]
	v_pk_fma_f32 v[186:187], v[112:113], v[152:153], v[128:129]
	v_fmac_f32_dpp v184, v176, v102 row_ror:1 row_mask:0xf bank_mask:0xf
	v_fmac_f32_dpp v185, v177, v103 row_ror:1 row_mask:0xf bank_mask:0xf
	v_fmac_f32_dpp v186, v178, v104 row_ror:1 row_mask:0xf bank_mask:0xf
	v_fmac_f32_dpp v187, v179, v105 row_ror:1 row_mask:0xf bank_mask:0xf
	v_fmac_f32_dpp v184, v180, v118 row_ror:15 row_mask:0xf bank_mask:0xf
	v_fmac_f32_dpp v185, v181, v119 row_ror:15 row_mask:0xf bank_mask:0xf
	v_fmac_f32_dpp v186, v182, v120 row_ror:15 row_mask:0xf bank_mask:0xf
	v_fmac_f32_dpp v187, v183, v121 row_ror:15 row_mask:0xf bank_mask:0xf
	v_pk_mul_f32 v[176:177], v[184:185], v[184:185]
	v_pk_mul_f32 v[178:179], v[186:187], v[186:187]
	v_pk_fma_f32 v[176:177], v[176:177], v[208:209], s[40:41] op_sel_hi:[1,0,0]
	v_pk_fma_f32 v[178:179], v[178:179], v[208:209], s[40:41] op_sel_hi:[1,0,0]
	v_pk_mul_f32 v[176:177], v[176:177], v[184:185]
	v_pk_mul_f32 v[178:179], v[178:179], v[186:187]
	v_exp_f32_e32 v176, v176
	v_exp_f32_e32 v177, v177
	v_exp_f32_e32 v178, v178
	v_exp_f32_e32 v179, v179
	v_add_f32_e32 v176, 1.0, v176
	v_add_f32_e32 v177, 1.0, v177
	v_add_f32_e32 v178, 1.0, v178
	v_add_f32_e32 v179, 1.0, v179
	v_rcp_f32_e32 v176, v176
	v_rcp_f32_e32 v177, v177
	v_rcp_f32_e32 v178, v178
	v_rcp_f32_e32 v179, v179
	v_pk_mul_f32 v[184:185], v[184:185], v[176:177]
	v_pk_mul_f32 v[186:187], v[186:187], v[178:179]
	v_pk_mul_f32 v[184:185], v[184:185], v[158:159]
	v_pk_mul_f32 v[186:187], v[186:187], v[160:161]
	v_cvt_pk_bf16_f32 v188, v184, v185
	v_cvt_pk_bf16_f32 v189, v186, v187
	v_cndmask_b32_e64 v176, v142, v84, s[8:9]
	v_cndmask_b32_e64 v177, v143, v85, s[8:9]
	v_cndmask_b32_e64 v178, v144, v86, s[8:9]
	v_cndmask_b32_e64 v179, v145, v87, s[8:9]
	v_cndmask_b32_e64 v180, v142, v130, s[4:5]
	v_cndmask_b32_e64 v181, v143, v131, s[4:5]
	v_cndmask_b32_e64 v182, v144, v132, s[4:5]
	v_cndmask_b32_e64 v183, v145, v133, s[4:5]
	v_pk_fma_f32 v[184:185], v[114:115], v[142:143], v[80:81]
	v_pk_fma_f32 v[186:187], v[116:117], v[144:145], v[82:83]
	v_fmac_f32_dpp v184, v176, v106 row_ror:1 row_mask:0xf bank_mask:0xf
	v_fmac_f32_dpp v185, v177, v107 row_ror:1 row_mask:0xf bank_mask:0xf
	v_fmac_f32_dpp v186, v178, v108 row_ror:1 row_mask:0xf bank_mask:0xf
	v_fmac_f32_dpp v187, v179, v109 row_ror:1 row_mask:0xf bank_mask:0xf
	v_fmac_f32_dpp v184, v180, v122 row_ror:15 row_mask:0xf bank_mask:0xf
	v_fmac_f32_dpp v185, v181, v123 row_ror:15 row_mask:0xf bank_mask:0xf
	v_fmac_f32_dpp v186, v182, v124 row_ror:15 row_mask:0xf bank_mask:0xf
	v_fmac_f32_dpp v187, v183, v125 row_ror:15 row_mask:0xf bank_mask:0xf
	v_pk_mul_f32 v[176:177], v[184:185], v[184:185]
	v_pk_mul_f32 v[178:179], v[186:187], v[186:187]
	v_pk_fma_f32 v[176:177], v[176:177], v[208:209], s[40:41] op_sel_hi:[1,0,0]
	v_pk_fma_f32 v[178:179], v[178:179], v[208:209], s[40:41] op_sel_hi:[1,0,0]
	v_pk_mul_f32 v[176:177], v[176:177], v[184:185]
	v_pk_mul_f32 v[178:179], v[178:179], v[186:187]
	v_exp_f32_e32 v176, v176
	v_exp_f32_e32 v177, v177
	v_exp_f32_e32 v178, v178
	v_exp_f32_e32 v179, v179
	v_add_f32_e32 v176, 1.0, v176
	v_add_f32_e32 v177, 1.0, v177
	v_add_f32_e32 v178, 1.0, v178
	v_add_f32_e32 v179, 1.0, v179
	v_rcp_f32_e32 v176, v176
	v_rcp_f32_e32 v177, v177
	v_rcp_f32_e32 v178, v178
	v_rcp_f32_e32 v179, v179
	v_pk_mul_f32 v[184:185], v[184:185], v[176:177]
	v_pk_mul_f32 v[186:187], v[186:187], v[178:179]
	v_pk_mul_f32 v[184:185], v[184:185], v[154:155]
	v_pk_mul_f32 v[186:187], v[186:187], v[156:157]
	v_cvt_pk_bf16_f32 v190, v184, v185
	v_cvt_pk_bf16_f32 v191, v186, v187
	v_or_b32_e32 v176, 16, v174
	v_mad_u32_u24 v176, v176, s44, v175
	global_store_dwordx4 v176, v[188:191], s[54:55]
	v_cndmask_b32_e64 v176, v134, v150, s[8:9]
	v_cndmask_b32_e64 v177, v135, v151, s[8:9]
	v_cndmask_b32_e64 v178, v136, v152, s[8:9]
	v_cndmask_b32_e64 v179, v137, v153, s[8:9]
	v_cndmask_b32_e64 v180, v134, v72, s[4:5]
	v_cndmask_b32_e64 v181, v135, v73, s[4:5]
	v_cndmask_b32_e64 v182, v136, v74, s[4:5]
	v_cndmask_b32_e64 v183, v137, v75, s[4:5]
	v_pk_fma_f32 v[184:185], v[110:111], v[134:135], v[126:127]
	v_pk_fma_f32 v[186:187], v[112:113], v[136:137], v[128:129]
	v_fmac_f32_dpp v184, v176, v102 row_ror:1 row_mask:0xf bank_mask:0xf
	v_fmac_f32_dpp v185, v177, v103 row_ror:1 row_mask:0xf bank_mask:0xf
	v_fmac_f32_dpp v186, v178, v104 row_ror:1 row_mask:0xf bank_mask:0xf
	v_fmac_f32_dpp v187, v179, v105 row_ror:1 row_mask:0xf bank_mask:0xf
	v_fmac_f32_dpp v184, v180, v118 row_ror:15 row_mask:0xf bank_mask:0xf
	v_fmac_f32_dpp v185, v181, v119 row_ror:15 row_mask:0xf bank_mask:0xf
	v_fmac_f32_dpp v186, v182, v120 row_ror:15 row_mask:0xf bank_mask:0xf
	v_fmac_f32_dpp v187, v183, v121 row_ror:15 row_mask:0xf bank_mask:0xf
	v_pk_mul_f32 v[176:177], v[184:185], v[184:185]
	v_pk_mul_f32 v[178:179], v[186:187], v[186:187]
	v_pk_fma_f32 v[176:177], v[176:177], v[208:209], s[40:41] op_sel_hi:[1,0,0]
	v_pk_fma_f32 v[178:179], v[178:179], v[208:209], s[40:41] op_sel_hi:[1,0,0]
	v_pk_mul_f32 v[176:177], v[176:177], v[184:185]
	v_pk_mul_f32 v[178:179], v[178:179], v[186:187]
	v_exp_f32_e32 v176, v176
	v_exp_f32_e32 v177, v177
	v_exp_f32_e32 v178, v178
	v_exp_f32_e32 v179, v179
	v_add_f32_e32 v176, 1.0, v176
	v_add_f32_e32 v177, 1.0, v177
	v_add_f32_e32 v178, 1.0, v178
	v_add_f32_e32 v179, 1.0, v179
	v_rcp_f32_e32 v176, v176
	v_rcp_f32_e32 v177, v177
	v_rcp_f32_e32 v178, v178
	v_rcp_f32_e32 v179, v179
	v_pk_mul_f32 v[184:185], v[184:185], v[176:177]
	v_pk_mul_f32 v[186:187], v[186:187], v[178:179]
	v_pk_mul_f32 v[184:185], v[184:185], v[146:147]
	v_pk_mul_f32 v[186:187], v[186:187], v[148:149]
	v_cvt_pk_bf16_f32 v188, v184, v185
	v_cvt_pk_bf16_f32 v189, v186, v187
	v_cndmask_b32_e64 v176, v130, v142, s[8:9]
	v_cndmask_b32_e64 v177, v131, v143, s[8:9]
	v_cndmask_b32_e64 v178, v132, v144, s[8:9]
	v_cndmask_b32_e64 v179, v133, v145, s[8:9]
	v_cndmask_b32_e64 v180, v130, v64, s[4:5]
	v_cndmask_b32_e64 v181, v131, v65, s[4:5]
	v_cndmask_b32_e64 v182, v132, v66, s[4:5]
	v_cndmask_b32_e64 v183, v133, v67, s[4:5]
	v_pk_fma_f32 v[184:185], v[114:115], v[130:131], v[80:81]
	v_pk_fma_f32 v[186:187], v[116:117], v[132:133], v[82:83]
	v_fmac_f32_dpp v184, v176, v106 row_ror:1 row_mask:0xf bank_mask:0xf
	v_fmac_f32_dpp v185, v177, v107 row_ror:1 row_mask:0xf bank_mask:0xf
	v_fmac_f32_dpp v186, v178, v108 row_ror:1 row_mask:0xf bank_mask:0xf
	v_fmac_f32_dpp v187, v179, v109 row_ror:1 row_mask:0xf bank_mask:0xf
	v_fmac_f32_dpp v184, v180, v122 row_ror:15 row_mask:0xf bank_mask:0xf
	v_fmac_f32_dpp v185, v181, v123 row_ror:15 row_mask:0xf bank_mask:0xf
	v_fmac_f32_dpp v186, v182, v124 row_ror:15 row_mask:0xf bank_mask:0xf
	v_fmac_f32_dpp v187, v183, v125 row_ror:15 row_mask:0xf bank_mask:0xf
	v_pk_mul_f32 v[176:177], v[184:185], v[184:185]
	v_pk_mul_f32 v[178:179], v[186:187], v[186:187]
	v_pk_fma_f32 v[176:177], v[176:177], v[208:209], s[40:41] op_sel_hi:[1,0,0]
	v_pk_fma_f32 v[178:179], v[178:179], v[208:209], s[40:41] op_sel_hi:[1,0,0]
	v_pk_mul_f32 v[176:177], v[176:177], v[184:185]
	v_pk_mul_f32 v[178:179], v[178:179], v[186:187]
	v_exp_f32_e32 v176, v176
	v_exp_f32_e32 v177, v177
	v_exp_f32_e32 v178, v178
	v_exp_f32_e32 v179, v179
	v_add_f32_e32 v176, 1.0, v176
	v_add_f32_e32 v177, 1.0, v177
	v_add_f32_e32 v178, 1.0, v178
	v_add_f32_e32 v179, 1.0, v179
	v_rcp_f32_e32 v176, v176
	v_rcp_f32_e32 v177, v177
	v_rcp_f32_e32 v178, v178
	v_rcp_f32_e32 v179, v179
	v_pk_mul_f32 v[184:185], v[184:185], v[176:177]
	v_pk_mul_f32 v[186:187], v[186:187], v[178:179]
	v_pk_mul_f32 v[184:185], v[184:185], v[138:139]
	v_pk_mul_f32 v[186:187], v[186:187], v[140:141]
	v_cvt_pk_bf16_f32 v190, v184, v185
	v_cvt_pk_bf16_f32 v191, v186, v187
	v_or_b32_e32 v176, 32, v174
	v_mad_u32_u24 v176, v176, s44, v175
	global_store_dwordx4 v176, v[188:191], s[54:55]
	v_cndmask_b32_e64 v176, v72, v134, s[8:9]
	v_cndmask_b32_e64 v177, v73, v135, s[8:9]
	v_cndmask_b32_e64 v178, v74, v136, s[8:9]
	v_cndmask_b32_e64 v179, v75, v137, s[8:9]
	v_cndmask_b32_e64 v180, v72, 0, s[4:5]
	v_cndmask_b32_e64 v181, v73, 0, s[4:5]
	v_cndmask_b32_e64 v182, v74, 0, s[4:5]
	v_cndmask_b32_e64 v183, v75, 0, s[4:5]
	v_pk_fma_f32 v[184:185], v[110:111], v[72:73], v[126:127]
	v_pk_fma_f32 v[186:187], v[112:113], v[74:75], v[128:129]
	v_fmac_f32_dpp v184, v176, v102 row_ror:1 row_mask:0xf bank_mask:0xf
	v_fmac_f32_dpp v185, v177, v103 row_ror:1 row_mask:0xf bank_mask:0xf
	v_fmac_f32_dpp v186, v178, v104 row_ror:1 row_mask:0xf bank_mask:0xf
	v_fmac_f32_dpp v187, v179, v105 row_ror:1 row_mask:0xf bank_mask:0xf
	v_fmac_f32_dpp v184, v180, v118 row_ror:15 row_mask:0xf bank_mask:0xf
	v_fmac_f32_dpp v185, v181, v119 row_ror:15 row_mask:0xf bank_mask:0xf
	v_fmac_f32_dpp v186, v182, v120 row_ror:15 row_mask:0xf bank_mask:0xf
	v_fmac_f32_dpp v187, v183, v121 row_ror:15 row_mask:0xf bank_mask:0xf
	v_pk_mul_f32 v[176:177], v[184:185], v[184:185]
	v_pk_mul_f32 v[178:179], v[186:187], v[186:187]
	v_pk_fma_f32 v[176:177], v[176:177], v[208:209], s[40:41] op_sel_hi:[1,0,0]
	v_pk_fma_f32 v[178:179], v[178:179], v[208:209], s[40:41] op_sel_hi:[1,0,0]
	v_pk_mul_f32 v[176:177], v[176:177], v[184:185]
	v_pk_mul_f32 v[178:179], v[178:179], v[186:187]
	v_exp_f32_e32 v176, v176
	v_exp_f32_e32 v177, v177
	v_exp_f32_e32 v178, v178
	v_exp_f32_e32 v179, v179
	v_add_f32_e32 v176, 1.0, v176
	v_add_f32_e32 v177, 1.0, v177
	v_add_f32_e32 v178, 1.0, v178
	v_add_f32_e32 v179, 1.0, v179
	v_rcp_f32_e32 v176, v176
	v_rcp_f32_e32 v177, v177
	v_rcp_f32_e32 v178, v178
	v_rcp_f32_e32 v179, v179
	v_pk_mul_f32 v[184:185], v[184:185], v[176:177]
	v_pk_mul_f32 v[186:187], v[186:187], v[178:179]
	v_pk_mul_f32 v[184:185], v[184:185], v[76:77]
	v_pk_mul_f32 v[186:187], v[186:187], v[78:79]
	v_cvt_pk_bf16_f32 v188, v184, v185
	v_cvt_pk_bf16_f32 v189, v186, v187
	v_cndmask_b32_e64 v176, v64, v130, s[8:9]
	v_cndmask_b32_e64 v177, v65, v131, s[8:9]
	v_cndmask_b32_e64 v178, v66, v132, s[8:9]
	v_cndmask_b32_e64 v179, v67, v133, s[8:9]
	v_cndmask_b32_e64 v180, v64, 0, s[4:5]
	v_cndmask_b32_e64 v181, v65, 0, s[4:5]
	v_cndmask_b32_e64 v182, v66, 0, s[4:5]
	v_cndmask_b32_e64 v183, v67, 0, s[4:5]
	v_pk_fma_f32 v[184:185], v[114:115], v[64:65], v[80:81]
	v_pk_fma_f32 v[186:187], v[116:117], v[66:67], v[82:83]
	v_fmac_f32_dpp v184, v176, v106 row_ror:1 row_mask:0xf bank_mask:0xf
	v_fmac_f32_dpp v185, v177, v107 row_ror:1 row_mask:0xf bank_mask:0xf
	v_fmac_f32_dpp v186, v178, v108 row_ror:1 row_mask:0xf bank_mask:0xf
	v_fmac_f32_dpp v187, v179, v109 row_ror:1 row_mask:0xf bank_mask:0xf
	v_fmac_f32_dpp v184, v180, v122 row_ror:15 row_mask:0xf bank_mask:0xf
	v_fmac_f32_dpp v185, v181, v123 row_ror:15 row_mask:0xf bank_mask:0xf
	v_fmac_f32_dpp v186, v182, v124 row_ror:15 row_mask:0xf bank_mask:0xf
	v_fmac_f32_dpp v187, v183, v125 row_ror:15 row_mask:0xf bank_mask:0xf
	v_pk_mul_f32 v[176:177], v[184:185], v[184:185]
	v_pk_mul_f32 v[178:179], v[186:187], v[186:187]
	v_pk_fma_f32 v[176:177], v[176:177], v[208:209], s[40:41] op_sel_hi:[1,0,0]
	v_pk_fma_f32 v[178:179], v[178:179], v[208:209], s[40:41] op_sel_hi:[1,0,0]
	v_pk_mul_f32 v[176:177], v[176:177], v[184:185]
	v_pk_mul_f32 v[178:179], v[178:179], v[186:187]
	v_exp_f32_e32 v176, v176
	v_exp_f32_e32 v177, v177
	v_exp_f32_e32 v178, v178
	v_exp_f32_e32 v179, v179
	v_add_f32_e32 v176, 1.0, v176
	v_add_f32_e32 v177, 1.0, v177
	v_add_f32_e32 v178, 1.0, v178
	v_add_f32_e32 v179, 1.0, v179
	v_rcp_f32_e32 v176, v176
	v_rcp_f32_e32 v177, v177
	v_rcp_f32_e32 v178, v178
	v_rcp_f32_e32 v179, v179
	v_pk_mul_f32 v[184:185], v[184:185], v[176:177]
	v_pk_mul_f32 v[186:187], v[186:187], v[178:179]
	v_pk_mul_f32 v[184:185], v[184:185], v[68:69]
	v_pk_mul_f32 v[186:187], v[186:187], v[70:71]
	v_cvt_pk_bf16_f32 v190, v184, v185
	v_cvt_pk_bf16_f32 v191, v186, v187
	v_or_b32_e32 v176, 48, v174
	v_mad_u32_u24 v176, v176, s44, v175
	s_and_saveexec_b64 s[38:39], s[10:11]
	global_store_dwordx4 v176, v[188:191], s[54:55]
	s_or_b64 exec, exec, s[38:39]
	v_cndmask_b32_e64 v176, v24, 0, s[8:9]
	v_cndmask_b32_e64 v177, v25, 0, s[8:9]
	v_cndmask_b32_e64 v178, v26, 0, s[8:9]
	v_cndmask_b32_e64 v179, v27, 0, s[8:9]
	v_cndmask_b32_e64 v180, v24, v52, s[4:5]
	v_cndmask_b32_e64 v181, v25, v53, s[4:5]
	v_cndmask_b32_e64 v182, v26, v54, s[4:5]
	v_cndmask_b32_e64 v183, v27, v55, s[4:5]
	v_pk_fma_f32 v[184:185], v[110:111], v[24:25], v[126:127]
	v_pk_fma_f32 v[186:187], v[112:113], v[26:27], v[128:129]
	v_fmac_f32_dpp v184, v176, v102 row_ror:1 row_mask:0xf bank_mask:0xf
	v_fmac_f32_dpp v185, v177, v103 row_ror:1 row_mask:0xf bank_mask:0xf
	v_fmac_f32_dpp v186, v178, v104 row_ror:1 row_mask:0xf bank_mask:0xf
	v_fmac_f32_dpp v187, v179, v105 row_ror:1 row_mask:0xf bank_mask:0xf
	v_fmac_f32_dpp v184, v180, v118 row_ror:15 row_mask:0xf bank_mask:0xf
	v_fmac_f32_dpp v185, v181, v119 row_ror:15 row_mask:0xf bank_mask:0xf
	v_fmac_f32_dpp v186, v182, v120 row_ror:15 row_mask:0xf bank_mask:0xf
	v_fmac_f32_dpp v187, v183, v121 row_ror:15 row_mask:0xf bank_mask:0xf
	v_pk_mul_f32 v[176:177], v[184:185], v[184:185]
	v_pk_mul_f32 v[178:179], v[186:187], v[186:187]
	v_pk_fma_f32 v[176:177], v[176:177], v[208:209], s[40:41] op_sel_hi:[1,0,0]
	v_pk_fma_f32 v[178:179], v[178:179], v[208:209], s[40:41] op_sel_hi:[1,0,0]
	v_pk_mul_f32 v[176:177], v[176:177], v[184:185]
	v_pk_mul_f32 v[178:179], v[178:179], v[186:187]
	v_exp_f32_e32 v176, v176
	v_exp_f32_e32 v177, v177
	v_exp_f32_e32 v178, v178
	v_exp_f32_e32 v179, v179
	v_add_f32_e32 v176, 1.0, v176
	v_add_f32_e32 v177, 1.0, v177
	v_add_f32_e32 v178, 1.0, v178
	v_add_f32_e32 v179, 1.0, v179
	v_rcp_f32_e32 v176, v176
	v_rcp_f32_e32 v177, v177
	v_rcp_f32_e32 v178, v178
	v_rcp_f32_e32 v179, v179
	v_pk_mul_f32 v[184:185], v[184:185], v[176:177]
	v_pk_mul_f32 v[186:187], v[186:187], v[178:179]
	v_pk_mul_f32 v[184:185], v[184:185], v[28:29]
	v_pk_mul_f32 v[186:187], v[186:187], v[30:31]
	v_cvt_pk_bf16_f32 v188, v184, v185
	v_cvt_pk_bf16_f32 v189, v186, v187
	v_cndmask_b32_e64 v176, v16, 0, s[8:9]
	v_cndmask_b32_e64 v177, v17, 0, s[8:9]
	v_cndmask_b32_e64 v178, v18, 0, s[8:9]
	v_cndmask_b32_e64 v179, v19, 0, s[8:9]
	v_cndmask_b32_e64 v180, v16, v44, s[4:5]
	v_cndmask_b32_e64 v181, v17, v45, s[4:5]
	v_cndmask_b32_e64 v182, v18, v46, s[4:5]
	v_cndmask_b32_e64 v183, v19, v47, s[4:5]
	v_pk_fma_f32 v[184:185], v[114:115], v[16:17], v[80:81]
	v_pk_fma_f32 v[186:187], v[116:117], v[18:19], v[82:83]
	v_fmac_f32_dpp v184, v176, v106 row_ror:1 row_mask:0xf bank_mask:0xf
	v_fmac_f32_dpp v185, v177, v107 row_ror:1 row_mask:0xf bank_mask:0xf
	v_fmac_f32_dpp v186, v178, v108 row_ror:1 row_mask:0xf bank_mask:0xf
	v_fmac_f32_dpp v187, v179, v109 row_ror:1 row_mask:0xf bank_mask:0xf
	v_fmac_f32_dpp v184, v180, v122 row_ror:15 row_mask:0xf bank_mask:0xf
	v_fmac_f32_dpp v185, v181, v123 row_ror:15 row_mask:0xf bank_mask:0xf
	v_fmac_f32_dpp v186, v182, v124 row_ror:15 row_mask:0xf bank_mask:0xf
	v_fmac_f32_dpp v187, v183, v125 row_ror:15 row_mask:0xf bank_mask:0xf
	v_pk_mul_f32 v[176:177], v[184:185], v[184:185]
	v_pk_mul_f32 v[178:179], v[186:187], v[186:187]
	v_pk_fma_f32 v[176:177], v[176:177], v[208:209], s[40:41] op_sel_hi:[1,0,0]
	v_pk_fma_f32 v[178:179], v[178:179], v[208:209], s[40:41] op_sel_hi:[1,0,0]
	v_pk_mul_f32 v[176:177], v[176:177], v[184:185]
	v_pk_mul_f32 v[178:179], v[178:179], v[186:187]
	v_exp_f32_e32 v176, v176
	v_exp_f32_e32 v177, v177
	v_exp_f32_e32 v178, v178
	v_exp_f32_e32 v179, v179
	v_add_f32_e32 v176, 1.0, v176
	v_add_f32_e32 v177, 1.0, v177
	v_add_f32_e32 v178, 1.0, v178
	v_add_f32_e32 v179, 1.0, v179
	v_rcp_f32_e32 v176, v176
	v_rcp_f32_e32 v177, v177
	v_rcp_f32_e32 v178, v178
	v_rcp_f32_e32 v179, v179
	v_pk_mul_f32 v[184:185], v[184:185], v[176:177]
	v_pk_mul_f32 v[186:187], v[186:187], v[178:179]
	v_pk_mul_f32 v[184:185], v[184:185], v[20:21]
	v_pk_mul_f32 v[186:187], v[186:187], v[22:23]
	v_cvt_pk_bf16_f32 v190, v184, v185
	v_cvt_pk_bf16_f32 v191, v186, v187
	v_or_b32_e32 v176, 0x80, v174
	v_mad_u32_u24 v176, v176, s44, v175
	s_and_saveexec_b64 s[38:39], s[6:7]
	global_store_dwordx4 v176, v[188:191], s[54:55]
	s_or_b64 exec, exec, s[38:39]
	v_cndmask_b32_e64 v176, v52, v24, s[8:9]
	v_cndmask_b32_e64 v177, v53, v25, s[8:9]
	v_cndmask_b32_e64 v178, v54, v26, s[8:9]
	v_cndmask_b32_e64 v179, v55, v27, s[8:9]
	v_cndmask_b32_e64 v180, v52, v36, s[4:5]
	v_cndmask_b32_e64 v181, v53, v37, s[4:5]
	v_cndmask_b32_e64 v182, v54, v38, s[4:5]
	v_cndmask_b32_e64 v183, v55, v39, s[4:5]
	v_pk_fma_f32 v[184:185], v[110:111], v[52:53], v[126:127]
	v_pk_fma_f32 v[186:187], v[112:113], v[54:55], v[128:129]
	v_fmac_f32_dpp v184, v176, v102 row_ror:1 row_mask:0xf bank_mask:0xf
	v_fmac_f32_dpp v185, v177, v103 row_ror:1 row_mask:0xf bank_mask:0xf
	v_fmac_f32_dpp v186, v178, v104 row_ror:1 row_mask:0xf bank_mask:0xf
	v_fmac_f32_dpp v187, v179, v105 row_ror:1 row_mask:0xf bank_mask:0xf
	v_fmac_f32_dpp v184, v180, v118 row_ror:15 row_mask:0xf bank_mask:0xf
	v_fmac_f32_dpp v185, v181, v119 row_ror:15 row_mask:0xf bank_mask:0xf
	v_fmac_f32_dpp v186, v182, v120 row_ror:15 row_mask:0xf bank_mask:0xf
	v_fmac_f32_dpp v187, v183, v121 row_ror:15 row_mask:0xf bank_mask:0xf
	v_pk_mul_f32 v[176:177], v[184:185], v[184:185]
	v_pk_mul_f32 v[178:179], v[186:187], v[186:187]
	v_pk_fma_f32 v[176:177], v[176:177], v[208:209], s[40:41] op_sel_hi:[1,0,0]
	v_pk_fma_f32 v[178:179], v[178:179], v[208:209], s[40:41] op_sel_hi:[1,0,0]
	v_pk_mul_f32 v[176:177], v[176:177], v[184:185]
	v_pk_mul_f32 v[178:179], v[178:179], v[186:187]
	v_exp_f32_e32 v176, v176
	v_exp_f32_e32 v177, v177
	v_exp_f32_e32 v178, v178
	v_exp_f32_e32 v179, v179
	v_add_f32_e32 v176, 1.0, v176
	v_add_f32_e32 v177, 1.0, v177
	v_add_f32_e32 v178, 1.0, v178
	v_add_f32_e32 v179, 1.0, v179
	v_rcp_f32_e32 v176, v176
	v_rcp_f32_e32 v177, v177
	v_rcp_f32_e32 v178, v178
	v_rcp_f32_e32 v179, v179
	v_pk_mul_f32 v[184:185], v[184:185], v[176:177]
	v_pk_mul_f32 v[186:187], v[186:187], v[178:179]
	v_pk_mul_f32 v[184:185], v[184:185], v[60:61]
	v_pk_mul_f32 v[186:187], v[186:187], v[62:63]
	v_cvt_pk_bf16_f32 v188, v184, v185
	v_cvt_pk_bf16_f32 v189, v186, v187
	v_cndmask_b32_e64 v176, v44, v16, s[8:9]
	v_cndmask_b32_e64 v177, v45, v17, s[8:9]
	v_cndmask_b32_e64 v178, v46, v18, s[8:9]
	v_cndmask_b32_e64 v179, v47, v19, s[8:9]
	v_cndmask_b32_e64 v180, v44, v32, s[4:5]
	v_cndmask_b32_e64 v181, v45, v33, s[4:5]
	v_cndmask_b32_e64 v182, v46, v34, s[4:5]
	v_cndmask_b32_e64 v183, v47, v35, s[4:5]
	v_pk_fma_f32 v[184:185], v[114:115], v[44:45], v[80:81]
	v_pk_fma_f32 v[186:187], v[116:117], v[46:47], v[82:83]
	v_fmac_f32_dpp v184, v176, v106 row_ror:1 row_mask:0xf bank_mask:0xf
	v_fmac_f32_dpp v185, v177, v107 row_ror:1 row_mask:0xf bank_mask:0xf
	v_fmac_f32_dpp v186, v178, v108 row_ror:1 row_mask:0xf bank_mask:0xf
	v_fmac_f32_dpp v187, v179, v109 row_ror:1 row_mask:0xf bank_mask:0xf
	v_fmac_f32_dpp v184, v180, v122 row_ror:15 row_mask:0xf bank_mask:0xf
	v_fmac_f32_dpp v185, v181, v123 row_ror:15 row_mask:0xf bank_mask:0xf
	v_fmac_f32_dpp v186, v182, v124 row_ror:15 row_mask:0xf bank_mask:0xf
	v_fmac_f32_dpp v187, v183, v125 row_ror:15 row_mask:0xf bank_mask:0xf
	v_pk_mul_f32 v[176:177], v[184:185], v[184:185]
	v_pk_mul_f32 v[178:179], v[186:187], v[186:187]
	v_pk_fma_f32 v[176:177], v[176:177], v[208:209], s[40:41] op_sel_hi:[1,0,0]
	v_pk_fma_f32 v[178:179], v[178:179], v[208:209], s[40:41] op_sel_hi:[1,0,0]
	v_pk_mul_f32 v[176:177], v[176:177], v[184:185]
	v_pk_mul_f32 v[178:179], v[178:179], v[186:187]
	v_exp_f32_e32 v176, v176
	v_exp_f32_e32 v177, v177
	v_exp_f32_e32 v178, v178
	v_exp_f32_e32 v179, v179
	v_add_f32_e32 v176, 1.0, v176
	v_add_f32_e32 v177, 1.0, v177
	v_add_f32_e32 v178, 1.0, v178
	v_add_f32_e32 v179, 1.0, v179
	v_rcp_f32_e32 v176, v176
	v_rcp_f32_e32 v177, v177
	v_rcp_f32_e32 v178, v178
	v_rcp_f32_e32 v179, v179
	v_pk_mul_f32 v[184:185], v[184:185], v[176:177]
	v_pk_mul_f32 v[186:187], v[186:187], v[178:179]
	v_pk_mul_f32 v[184:185], v[184:185], v[56:57]
	v_pk_mul_f32 v[186:187], v[186:187], v[58:59]
	v_cvt_pk_bf16_f32 v190, v184, v185
	v_cvt_pk_bf16_f32 v191, v186, v187
	v_or_b32_e32 v176, 0x90, v174
	v_mad_u32_u24 v176, v176, s44, v175
	global_store_dwordx4 v176, v[188:191], s[54:55]
	v_cndmask_b32_e64 v176, v36, v52, s[8:9]
	v_cndmask_b32_e64 v177, v37, v53, s[8:9]
	v_cndmask_b32_e64 v178, v38, v54, s[8:9]
	v_cndmask_b32_e64 v179, v39, v55, s[8:9]
	v_cndmask_b32_e64 v180, v36, v8, s[4:5]
	v_cndmask_b32_e64 v181, v37, v9, s[4:5]
	v_cndmask_b32_e64 v182, v38, v10, s[4:5]
	v_cndmask_b32_e64 v183, v39, v11, s[4:5]
	v_pk_fma_f32 v[184:185], v[110:111], v[36:37], v[126:127]
	v_pk_fma_f32 v[186:187], v[112:113], v[38:39], v[128:129]
	v_fmac_f32_dpp v184, v176, v102 row_ror:1 row_mask:0xf bank_mask:0xf
	v_fmac_f32_dpp v185, v177, v103 row_ror:1 row_mask:0xf bank_mask:0xf
	v_fmac_f32_dpp v186, v178, v104 row_ror:1 row_mask:0xf bank_mask:0xf
	v_fmac_f32_dpp v187, v179, v105 row_ror:1 row_mask:0xf bank_mask:0xf
	v_fmac_f32_dpp v184, v180, v118 row_ror:15 row_mask:0xf bank_mask:0xf
	v_fmac_f32_dpp v185, v181, v119 row_ror:15 row_mask:0xf bank_mask:0xf
	v_fmac_f32_dpp v186, v182, v120 row_ror:15 row_mask:0xf bank_mask:0xf
	v_fmac_f32_dpp v187, v183, v121 row_ror:15 row_mask:0xf bank_mask:0xf
	v_pk_mul_f32 v[176:177], v[184:185], v[184:185]
	v_pk_mul_f32 v[178:179], v[186:187], v[186:187]
	v_pk_fma_f32 v[176:177], v[176:177], v[208:209], s[40:41] op_sel_hi:[1,0,0]
	v_pk_fma_f32 v[178:179], v[178:179], v[208:209], s[40:41] op_sel_hi:[1,0,0]
	v_pk_mul_f32 v[176:177], v[176:177], v[184:185]
	v_pk_mul_f32 v[178:179], v[178:179], v[186:187]
	v_exp_f32_e32 v176, v176
	v_exp_f32_e32 v177, v177
	v_exp_f32_e32 v178, v178
	v_exp_f32_e32 v179, v179
	v_add_f32_e32 v176, 1.0, v176
	v_add_f32_e32 v177, 1.0, v177
	v_add_f32_e32 v178, 1.0, v178
	v_add_f32_e32 v179, 1.0, v179
	v_rcp_f32_e32 v176, v176
	v_rcp_f32_e32 v177, v177
	v_rcp_f32_e32 v178, v178
	v_rcp_f32_e32 v179, v179
	v_pk_mul_f32 v[184:185], v[184:185], v[176:177]
	v_pk_mul_f32 v[186:187], v[186:187], v[178:179]
	v_pk_mul_f32 v[184:185], v[184:185], v[48:49]
	v_pk_mul_f32 v[186:187], v[186:187], v[50:51]
	v_cvt_pk_bf16_f32 v188, v184, v185
	v_cvt_pk_bf16_f32 v189, v186, v187
	v_cndmask_b32_e64 v176, v32, v44, s[8:9]
	v_cndmask_b32_e64 v177, v33, v45, s[8:9]
	v_cndmask_b32_e64 v178, v34, v46, s[8:9]
	v_cndmask_b32_e64 v179, v35, v47, s[8:9]
	v_cndmask_b32_e64 v180, v32, v0, s[4:5]
	v_cndmask_b32_e64 v181, v33, v1, s[4:5]
	v_cndmask_b32_e64 v182, v34, v2, s[4:5]
	v_cndmask_b32_e64 v183, v35, v3, s[4:5]
	v_pk_fma_f32 v[184:185], v[114:115], v[32:33], v[80:81]
	v_pk_fma_f32 v[186:187], v[116:117], v[34:35], v[82:83]
	v_fmac_f32_dpp v184, v176, v106 row_ror:1 row_mask:0xf bank_mask:0xf
	v_fmac_f32_dpp v185, v177, v107 row_ror:1 row_mask:0xf bank_mask:0xf
	v_fmac_f32_dpp v186, v178, v108 row_ror:1 row_mask:0xf bank_mask:0xf
	v_fmac_f32_dpp v187, v179, v109 row_ror:1 row_mask:0xf bank_mask:0xf
	v_fmac_f32_dpp v184, v180, v122 row_ror:15 row_mask:0xf bank_mask:0xf
	v_fmac_f32_dpp v185, v181, v123 row_ror:15 row_mask:0xf bank_mask:0xf
	v_fmac_f32_dpp v186, v182, v124 row_ror:15 row_mask:0xf bank_mask:0xf
	v_fmac_f32_dpp v187, v183, v125 row_ror:15 row_mask:0xf bank_mask:0xf
	v_pk_mul_f32 v[176:177], v[184:185], v[184:185]
	v_pk_mul_f32 v[178:179], v[186:187], v[186:187]
	v_pk_fma_f32 v[176:177], v[176:177], v[208:209], s[40:41] op_sel_hi:[1,0,0]
	v_pk_fma_f32 v[178:179], v[178:179], v[208:209], s[40:41] op_sel_hi:[1,0,0]
	v_pk_mul_f32 v[176:177], v[176:177], v[184:185]
	v_pk_mul_f32 v[178:179], v[178:179], v[186:187]
	v_exp_f32_e32 v176, v176
	v_exp_f32_e32 v177, v177
	v_exp_f32_e32 v178, v178
	v_exp_f32_e32 v179, v179
	v_add_f32_e32 v176, 1.0, v176
	v_add_f32_e32 v177, 1.0, v177
	v_add_f32_e32 v178, 1.0, v178
	v_add_f32_e32 v179, 1.0, v179
	v_rcp_f32_e32 v176, v176
	v_rcp_f32_e32 v177, v177
	v_rcp_f32_e32 v178, v178
	v_rcp_f32_e32 v179, v179
	v_pk_mul_f32 v[184:185], v[184:185], v[176:177]
	v_pk_mul_f32 v[186:187], v[186:187], v[178:179]
	v_pk_mul_f32 v[184:185], v[184:185], v[40:41]
	v_pk_mul_f32 v[186:187], v[186:187], v[42:43]
	v_cvt_pk_bf16_f32 v190, v184, v185
	v_cvt_pk_bf16_f32 v191, v186, v187
	v_or_b32_e32 v176, 0xa0, v174
	v_mad_u32_u24 v176, v176, s44, v175
	global_store_dwordx4 v176, v[188:191], s[54:55]
	v_cndmask_b32_e64 v176, v8, v36, s[8:9]
	v_cndmask_b32_e64 v177, v9, v37, s[8:9]
	v_cndmask_b32_e64 v178, v10, v38, s[8:9]
	v_cndmask_b32_e64 v179, v11, v39, s[8:9]
	v_cndmask_b32_e64 v180, v8, 0, s[4:5]
	v_cndmask_b32_e64 v181, v9, 0, s[4:5]
	v_cndmask_b32_e64 v182, v10, 0, s[4:5]
	v_cndmask_b32_e64 v183, v11, 0, s[4:5]
	v_pk_fma_f32 v[184:185], v[110:111], v[8:9], v[126:127]
	v_pk_fma_f32 v[186:187], v[112:113], v[10:11], v[128:129]
	v_fmac_f32_dpp v184, v176, v102 row_ror:1 row_mask:0xf bank_mask:0xf
	v_fmac_f32_dpp v185, v177, v103 row_ror:1 row_mask:0xf bank_mask:0xf
	v_fmac_f32_dpp v186, v178, v104 row_ror:1 row_mask:0xf bank_mask:0xf
	v_fmac_f32_dpp v187, v179, v105 row_ror:1 row_mask:0xf bank_mask:0xf
	v_fmac_f32_dpp v184, v180, v118 row_ror:15 row_mask:0xf bank_mask:0xf
	v_fmac_f32_dpp v185, v181, v119 row_ror:15 row_mask:0xf bank_mask:0xf
	v_fmac_f32_dpp v186, v182, v120 row_ror:15 row_mask:0xf bank_mask:0xf
	v_fmac_f32_dpp v187, v183, v121 row_ror:15 row_mask:0xf bank_mask:0xf
	v_pk_mul_f32 v[176:177], v[184:185], v[184:185]
	v_pk_mul_f32 v[178:179], v[186:187], v[186:187]
	v_pk_fma_f32 v[176:177], v[176:177], v[208:209], s[40:41] op_sel_hi:[1,0,0]
	v_pk_fma_f32 v[178:179], v[178:179], v[208:209], s[40:41] op_sel_hi:[1,0,0]
	v_pk_mul_f32 v[176:177], v[176:177], v[184:185]
	v_pk_mul_f32 v[178:179], v[178:179], v[186:187]
	v_exp_f32_e32 v176, v176
	v_exp_f32_e32 v177, v177
	v_exp_f32_e32 v178, v178
	v_exp_f32_e32 v179, v179
	v_add_f32_e32 v176, 1.0, v176
	v_add_f32_e32 v177, 1.0, v177
	v_add_f32_e32 v178, 1.0, v178
	v_add_f32_e32 v179, 1.0, v179
	v_rcp_f32_e32 v176, v176
	v_rcp_f32_e32 v177, v177
	v_rcp_f32_e32 v178, v178
	v_rcp_f32_e32 v179, v179
	v_pk_mul_f32 v[184:185], v[184:185], v[176:177]
	v_pk_mul_f32 v[186:187], v[186:187], v[178:179]
	v_pk_mul_f32 v[184:185], v[184:185], v[12:13]
	v_pk_mul_f32 v[186:187], v[186:187], v[14:15]
	v_cvt_pk_bf16_f32 v188, v184, v185
	v_cvt_pk_bf16_f32 v189, v186, v187
	v_cndmask_b32_e64 v176, v0, v32, s[8:9]
	v_cndmask_b32_e64 v177, v1, v33, s[8:9]
	v_cndmask_b32_e64 v178, v2, v34, s[8:9]
	v_cndmask_b32_e64 v179, v3, v35, s[8:9]
	v_cndmask_b32_e64 v180, v0, 0, s[4:5]
	v_cndmask_b32_e64 v181, v1, 0, s[4:5]
	v_cndmask_b32_e64 v182, v2, 0, s[4:5]
	v_cndmask_b32_e64 v183, v3, 0, s[4:5]
	v_pk_fma_f32 v[184:185], v[114:115], v[0:1], v[80:81]
	v_pk_fma_f32 v[186:187], v[116:117], v[2:3], v[82:83]
	v_fmac_f32_dpp v184, v176, v106 row_ror:1 row_mask:0xf bank_mask:0xf
	v_fmac_f32_dpp v185, v177, v107 row_ror:1 row_mask:0xf bank_mask:0xf
	v_fmac_f32_dpp v186, v178, v108 row_ror:1 row_mask:0xf bank_mask:0xf
	v_fmac_f32_dpp v187, v179, v109 row_ror:1 row_mask:0xf bank_mask:0xf
	v_fmac_f32_dpp v184, v180, v122 row_ror:15 row_mask:0xf bank_mask:0xf
	v_fmac_f32_dpp v185, v181, v123 row_ror:15 row_mask:0xf bank_mask:0xf
	v_fmac_f32_dpp v186, v182, v124 row_ror:15 row_mask:0xf bank_mask:0xf
	v_fmac_f32_dpp v187, v183, v125 row_ror:15 row_mask:0xf bank_mask:0xf
	v_pk_mul_f32 v[176:177], v[184:185], v[184:185]
	v_pk_mul_f32 v[178:179], v[186:187], v[186:187]
	v_pk_fma_f32 v[176:177], v[176:177], v[208:209], s[40:41] op_sel_hi:[1,0,0]
	v_pk_fma_f32 v[178:179], v[178:179], v[208:209], s[40:41] op_sel_hi:[1,0,0]
	v_pk_mul_f32 v[176:177], v[176:177], v[184:185]
	v_pk_mul_f32 v[178:179], v[178:179], v[186:187]
	v_exp_f32_e32 v176, v176
	v_exp_f32_e32 v177, v177
	v_exp_f32_e32 v178, v178
	v_exp_f32_e32 v179, v179
	v_add_f32_e32 v176, 1.0, v176
	v_add_f32_e32 v177, 1.0, v177
	v_add_f32_e32 v178, 1.0, v178
	v_add_f32_e32 v179, 1.0, v179
	v_rcp_f32_e32 v176, v176
	v_rcp_f32_e32 v177, v177
	v_rcp_f32_e32 v178, v178
	v_rcp_f32_e32 v179, v179
	v_pk_mul_f32 v[184:185], v[184:185], v[176:177]
	v_pk_mul_f32 v[186:187], v[186:187], v[178:179]
	v_pk_mul_f32 v[184:185], v[184:185], v[4:5]
	v_pk_mul_f32 v[186:187], v[186:187], v[6:7]
	v_cvt_pk_bf16_f32 v190, v184, v185
	v_cvt_pk_bf16_f32 v191, v186, v187
	v_or_b32_e32 v176, 0xb0, v174
	v_mad_u32_u24 v176, v176, s44, v175
	s_and_saveexec_b64 s[38:39], s[10:11]
	global_store_dwordx4 v176, v[188:191], s[54:55]
	s_or_b64 exec, exec, s[38:39]
